# SwiGLU epilogue rewritten by hand (packed scale/+1, 32-bit store offsets); tile accumulator clears as 64 v_mov_b64
# speedup vs baseline: 1.0086x; 1.0055x over previous
.LBB0_102:
	s_ashr_i32 s19, s18, 31
	s_lshl_b64 s[20:21], s[18:19], 19
	s_add_u32 s20, s52, s20
	s_addc_u32 s21, s47, s21
	s_and_b64 s[22:23], s[6:7], exec
	s_cselect_b32 s0, s21, s25
	s_cselect_b32 s19, s20, s24
	s_ashr_i32 s17, s16, 31
	s_lshl_b64 s[22:23], s[16:17], 19
	s_add_u32 s22, s54, s22
	s_addc_u32 s23, s53, s23
	s_and_b64 s[36:37], s[6:7], exec
	s_cselect_b32 s17, s23, s29
	s_cselect_b32 s35, s22, s28
	s_add_u32 s24, s24, 0x40080
	s_addc_u32 s25, s25, 0
	s_add_u32 s48, s28, 0x100
	v_mov_b64_e32 v[2:3], 0
	s_addc_u32 s49, s29, 0
	s_mov_b32 s67, -2
	v_mov_b64_e32 v[4:5], 0
	v_mov_b64_e32 v[6:7], 0
	v_mov_b64_e32 v[8:9], 0
	v_mov_b64_e32 v[10:11], 0
	v_mov_b64_e32 v[12:13], 0
	v_mov_b64_e32 v[14:15], 0
	v_mov_b64_e32 v[16:17], 0
	v_mov_b64_e32 v[18:19], 0
	v_mov_b64_e32 v[20:21], 0
	v_mov_b64_e32 v[22:23], 0
	v_mov_b64_e32 v[24:25], 0
	v_mov_b64_e32 v[26:27], 0
	v_mov_b64_e32 v[28:29], 0
	v_mov_b64_e32 v[30:31], 0
	v_mov_b64_e32 v[32:33], 0
	v_mov_b64_e32 v[34:35], 0
	v_mov_b64_e32 v[36:37], 0
	v_mov_b64_e32 v[38:39], 0
	v_mov_b64_e32 v[40:41], 0
	v_mov_b64_e32 v[42:43], 0
	v_mov_b64_e32 v[44:45], 0
	v_mov_b64_e32 v[46:47], 0
	v_mov_b64_e32 v[48:49], 0
	v_mov_b64_e32 v[50:51], 0
	v_mov_b64_e32 v[52:53], 0
	v_mov_b64_e32 v[54:55], 0
	v_mov_b64_e32 v[56:57], 0
	v_mov_b64_e32 v[58:59], 0
	v_mov_b64_e32 v[60:61], 0
	v_mov_b64_e32 v[62:63], 0
	v_mov_b64_e32 v[64:65], 0
	v_mov_b64_e32 v[66:67], 0
	v_mov_b64_e32 v[68:69], 0
	v_mov_b64_e32 v[70:71], 0
	v_mov_b64_e32 v[72:73], 0
	v_mov_b64_e32 v[74:75], 0
	v_mov_b64_e32 v[76:77], 0
	v_mov_b64_e32 v[78:79], 0
	v_mov_b64_e32 v[80:81], 0
	v_mov_b64_e32 v[82:83], 0
	v_mov_b64_e32 v[84:85], 0
	v_mov_b64_e32 v[86:87], 0
	v_mov_b64_e32 v[88:89], 0
	v_mov_b64_e32 v[90:91], 0
	v_mov_b64_e32 v[92:93], 0
	v_mov_b64_e32 v[94:95], 0
	v_mov_b64_e32 v[96:97], 0
	v_mov_b64_e32 v[98:99], 0
	v_mov_b64_e32 v[100:101], 0
	v_mov_b64_e32 v[102:103], 0
	v_mov_b64_e32 v[104:105], 0
	v_mov_b64_e32 v[106:107], 0
	v_mov_b64_e32 v[108:109], 0
	v_mov_b64_e32 v[110:111], 0
	v_mov_b64_e32 v[112:113], 0
	v_mov_b64_e32 v[114:115], 0
	v_mov_b64_e32 v[116:117], 0
	v_mov_b64_e32 v[118:119], 0
	v_mov_b64_e32 v[120:121], 0
	v_mov_b64_e32 v[122:123], 0
	v_mov_b64_e32 v[124:125], 0
	v_mov_b64_e32 v[126:127], 0
	v_mov_b64_e32 v[128:129], 0

.LBB0_248:
	s_ashr_i32 s21, s20, 31
	s_lshl_b64 s[22:23], s[20:21], 19
	v_readlane_b32 s24, v254, 8
	v_readlane_b32 s25, v254, 9
	s_add_u32 s22, s24, s22
	s_addc_u32 s23, s25, s23
	s_and_b64 s[24:25], s[6:7], exec
	s_cselect_b32 s21, s23, s9
	s_cselect_b32 s47, s22, s8
	s_ashr_i32 s19, s18, 31
	s_lshl_b64 s[24:25], s[18:19], 19
	s_add_u32 s24, s0, s24
	s_addc_u32 s25, s38, s25
	s_and_b64 s[36:37], s[6:7], exec
	s_cselect_b32 s19, s25, s29
	s_cselect_b32 s48, s24, s28
	s_add_u32 s8, s8, 0x40080
	s_addc_u32 s9, s9, 0
	s_add_u32 s49, s28, 0x100
	v_mov_b64_e32 v[2:3], 0
	s_addc_u32 s55, s29, 0
	s_mov_b32 s56, -2
	v_mov_b64_e32 v[4:5], 0
	v_mov_b64_e32 v[6:7], 0
	v_mov_b64_e32 v[8:9], 0
	v_mov_b64_e32 v[10:11], 0
	v_mov_b64_e32 v[12:13], 0
	v_mov_b64_e32 v[14:15], 0
	v_mov_b64_e32 v[16:17], 0
	v_mov_b64_e32 v[18:19], 0
	v_mov_b64_e32 v[20:21], 0
	v_mov_b64_e32 v[22:23], 0
	v_mov_b64_e32 v[24:25], 0
	v_mov_b64_e32 v[26:27], 0
	v_mov_b64_e32 v[28:29], 0
	v_mov_b64_e32 v[30:31], 0
	v_mov_b64_e32 v[32:33], 0
	v_mov_b64_e32 v[34:35], 0
	v_mov_b64_e32 v[36:37], 0
	v_mov_b64_e32 v[38:39], 0
	v_mov_b64_e32 v[40:41], 0
	v_mov_b64_e32 v[42:43], 0
	v_mov_b64_e32 v[44:45], 0
	v_mov_b64_e32 v[46:47], 0
	v_mov_b64_e32 v[48:49], 0
	v_mov_b64_e32 v[50:51], 0
	v_mov_b64_e32 v[52:53], 0
	v_mov_b64_e32 v[54:55], 0
	v_mov_b64_e32 v[56:57], 0
	v_mov_b64_e32 v[58:59], 0
	v_mov_b64_e32 v[60:61], 0
	v_mov_b64_e32 v[62:63], 0
	v_mov_b64_e32 v[64:65], 0
	v_mov_b64_e32 v[66:67], 0
	v_mov_b64_e32 v[68:69], 0
	v_mov_b64_e32 v[70:71], 0
	v_mov_b64_e32 v[72:73], 0
	v_mov_b64_e32 v[74:75], 0
	v_mov_b64_e32 v[76:77], 0
	v_mov_b64_e32 v[78:79], 0
	v_mov_b64_e32 v[80:81], 0
	v_mov_b64_e32 v[82:83], 0
	v_mov_b64_e32 v[84:85], 0
	v_mov_b64_e32 v[86:87], 0
	v_mov_b64_e32 v[88:89], 0
	v_mov_b64_e32 v[90:91], 0
	v_mov_b64_e32 v[92:93], 0
	v_mov_b64_e32 v[94:95], 0
	v_mov_b64_e32 v[96:97], 0
	v_mov_b64_e32 v[98:99], 0
	v_mov_b64_e32 v[100:101], 0
	v_mov_b64_e32 v[102:103], 0
	v_mov_b64_e32 v[104:105], 0
	v_mov_b64_e32 v[106:107], 0
	v_mov_b64_e32 v[108:109], 0
	v_mov_b64_e32 v[110:111], 0
	v_mov_b64_e32 v[112:113], 0
	v_mov_b64_e32 v[114:115], 0
	v_mov_b64_e32 v[116:117], 0
	v_mov_b64_e32 v[118:119], 0
	v_mov_b64_e32 v[120:121], 0
	v_mov_b64_e32 v[122:123], 0
	v_mov_b64_e32 v[124:125], 0
	v_mov_b64_e32 v[126:127], 0
	v_mov_b64_e32 v[128:129], 0

.Lrn_nodual_7:
.Lrn_tail:
	s_mov_b64 s[52:53], s[10:11]
	s_mov_b64 s[54:55], s[14:15]
	s_mov_b64 s[56:57], s[28:29]
	s_mov_b64 s[58:59], s[74:75]
	s_mov_b64 s[60:61], s[80:81]
	s_mov_b64 s[62:63], s[84:85]
	v_readlane_b32 s48, v253, 56
	v_readlane_b32 s49, v253, 57
	v_readlane_b32 s50, v253, 58
	v_readlane_b32 s51, v253, 59
	v_readlane_b32 s8, v254, 39
	v_readlane_b32 s9, v254, 40
	s_branch .LBB0_509

.LBB0_659:
	s_add_u32 s28, s28, 0x80
	s_addc_u32 s29, s29, 0
	s_add_u32 s34, s36, 0x100
	v_mov_b64_e32 v[2:3], 0
	s_addc_u32 s35, s37, 0
	s_mov_b32 s36, 0
	v_mov_b64_e32 v[4:5], 0
	v_mov_b64_e32 v[6:7], 0
	v_mov_b64_e32 v[8:9], 0
	v_mov_b64_e32 v[10:11], 0
	v_mov_b64_e32 v[12:13], 0
	v_mov_b64_e32 v[14:15], 0
	v_mov_b64_e32 v[16:17], 0
	v_mov_b64_e32 v[18:19], 0
	v_mov_b64_e32 v[20:21], 0
	v_mov_b64_e32 v[22:23], 0
	v_mov_b64_e32 v[24:25], 0
	v_mov_b64_e32 v[26:27], 0
	v_mov_b64_e32 v[28:29], 0
	v_mov_b64_e32 v[30:31], 0
	v_mov_b64_e32 v[32:33], 0
	v_mov_b64_e32 v[34:35], 0
	v_mov_b64_e32 v[36:37], 0
	v_mov_b64_e32 v[38:39], 0
	v_mov_b64_e32 v[40:41], 0
	v_mov_b64_e32 v[42:43], 0
	v_mov_b64_e32 v[44:45], 0
	v_mov_b64_e32 v[46:47], 0
	v_mov_b64_e32 v[48:49], 0
	v_mov_b64_e32 v[50:51], 0
	v_mov_b64_e32 v[52:53], 0
	v_mov_b64_e32 v[54:55], 0
	v_mov_b64_e32 v[56:57], 0
	v_mov_b64_e32 v[58:59], 0
	v_mov_b64_e32 v[60:61], 0
	v_mov_b64_e32 v[62:63], 0
	v_mov_b64_e32 v[64:65], 0
	v_mov_b64_e32 v[66:67], 0
	v_mov_b64_e32 v[68:69], 0
	v_mov_b64_e32 v[70:71], 0
	v_mov_b64_e32 v[72:73], 0
	v_mov_b64_e32 v[74:75], 0
	v_mov_b64_e32 v[76:77], 0
	v_mov_b64_e32 v[78:79], 0
	v_mov_b64_e32 v[80:81], 0
	v_mov_b64_e32 v[82:83], 0
	v_mov_b64_e32 v[84:85], 0
	v_mov_b64_e32 v[86:87], 0
	v_mov_b64_e32 v[88:89], 0
	v_mov_b64_e32 v[90:91], 0
	v_mov_b64_e32 v[92:93], 0
	v_mov_b64_e32 v[94:95], 0
	v_mov_b64_e32 v[96:97], 0
	v_mov_b64_e32 v[98:99], 0
	v_mov_b64_e32 v[100:101], 0
	v_mov_b64_e32 v[102:103], 0
	v_mov_b64_e32 v[104:105], 0
	v_mov_b64_e32 v[106:107], 0
	v_mov_b64_e32 v[108:109], 0
	v_mov_b64_e32 v[110:111], 0
	v_mov_b64_e32 v[112:113], 0
	v_mov_b64_e32 v[114:115], 0
	v_mov_b64_e32 v[116:117], 0
	v_mov_b64_e32 v[118:119], 0
	v_mov_b64_e32 v[120:121], 0
	v_mov_b64_e32 v[122:123], 0
	v_mov_b64_e32 v[124:125], 0
	v_mov_b64_e32 v[126:127], 0
	v_mov_b64_e32 v[128:129], 0

.LBB0_683:
	s_ashr_i32 s15, s14, 31
	s_lshl_b64 s[16:17], s[14:15], 19
	v_readlane_b32 s18, v254, 8
	v_readlane_b32 s19, v254, 9
	s_add_u32 s16, s18, s16
	s_addc_u32 s17, s19, s17
	s_and_b64 s[18:19], s[6:7], exec
	s_cselect_b32 s15, s17, s21
	s_cselect_b32 s43, s16, s20
	s_ashr_i32 s13, s12, 31
	s_lshl_b64 s[18:19], s[12:13], 19
	s_add_u32 s18, s0, s18
	s_addc_u32 s19, s28, s19
	s_and_b64 s[24:25], s[6:7], exec
	s_cselect_b32 s13, s19, s23
	s_cselect_b32 s47, s18, s22
	s_add_u32 s20, s20, 0x40080
	s_addc_u32 s21, s21, 0
	s_add_u32 s48, s22, 0x100
	v_mov_b64_e32 v[2:3], 0
	s_addc_u32 s49, s23, 0
	s_mov_b32 s50, -2
	v_mov_b64_e32 v[4:5], 0
	v_mov_b64_e32 v[6:7], 0
	v_mov_b64_e32 v[8:9], 0
	v_mov_b64_e32 v[10:11], 0
	v_mov_b64_e32 v[12:13], 0
	v_mov_b64_e32 v[14:15], 0
	v_mov_b64_e32 v[16:17], 0
	v_mov_b64_e32 v[18:19], 0
	v_mov_b64_e32 v[20:21], 0
	v_mov_b64_e32 v[22:23], 0
	v_mov_b64_e32 v[24:25], 0
	v_mov_b64_e32 v[26:27], 0
	v_mov_b64_e32 v[28:29], 0
	v_mov_b64_e32 v[30:31], 0
	v_mov_b64_e32 v[32:33], 0
	v_mov_b64_e32 v[34:35], 0
	v_mov_b64_e32 v[36:37], 0
	v_mov_b64_e32 v[38:39], 0
	v_mov_b64_e32 v[40:41], 0
	v_mov_b64_e32 v[42:43], 0
	v_mov_b64_e32 v[44:45], 0
	v_mov_b64_e32 v[46:47], 0
	v_mov_b64_e32 v[48:49], 0
	v_mov_b64_e32 v[50:51], 0
	v_mov_b64_e32 v[52:53], 0
	v_mov_b64_e32 v[54:55], 0
	v_mov_b64_e32 v[56:57], 0
	v_mov_b64_e32 v[58:59], 0
	v_mov_b64_e32 v[60:61], 0
	v_mov_b64_e32 v[62:63], 0
	v_mov_b64_e32 v[64:65], 0
	v_mov_b64_e32 v[66:67], 0
	v_mov_b64_e32 v[68:69], 0
	v_mov_b64_e32 v[70:71], 0
	v_mov_b64_e32 v[72:73], 0
	v_mov_b64_e32 v[74:75], 0
	v_mov_b64_e32 v[76:77], 0
	v_mov_b64_e32 v[78:79], 0
	v_mov_b64_e32 v[80:81], 0
	v_mov_b64_e32 v[82:83], 0
	v_mov_b64_e32 v[84:85], 0
	v_mov_b64_e32 v[86:87], 0
	v_mov_b64_e32 v[88:89], 0
	v_mov_b64_e32 v[90:91], 0
	v_mov_b64_e32 v[92:93], 0
	v_mov_b64_e32 v[94:95], 0
	v_mov_b64_e32 v[96:97], 0
	v_mov_b64_e32 v[98:99], 0
	v_mov_b64_e32 v[100:101], 0
	v_mov_b64_e32 v[102:103], 0
	v_mov_b64_e32 v[104:105], 0
	v_mov_b64_e32 v[106:107], 0
	v_mov_b64_e32 v[108:109], 0
	v_mov_b64_e32 v[110:111], 0
	v_mov_b64_e32 v[112:113], 0
	v_mov_b64_e32 v[114:115], 0
	v_mov_b64_e32 v[116:117], 0
	v_mov_b64_e32 v[118:119], 0
	v_mov_b64_e32 v[120:121], 0
	v_mov_b64_e32 v[122:123], 0
	v_mov_b64_e32 v[124:125], 0
	v_mov_b64_e32 v[126:127], 0
	v_mov_b64_e32 v[128:129], 0

.LBB0_687:
	v_readlane_b32 s20, v254, 12
	v_readlane_b32 s21, v254, 13
	s_movk_i32 s13, 0x1600
	v_lshl_add_u32 v146, s35, 8, v142
	v_lshl_or_b32 v147, s34, 7, v144
	v_mov_b32_e32 v148, 0xbfb8aa3b
	v_mov_b32_e32 v149, 0xbfb8aa3b
	v_mul_u32_u24_e32 v146, s13, v146
	v_lshl_add_u32 v146, v147, 1, v146
	v_pk_mul_f32 v[150:151], v[126:127], v[148:149]
	v_pk_mul_f32 v[152:153], v[128:129], v[148:149]
	v_pk_mul_f32 v[154:155], v[118:119], v[148:149]
	v_pk_mul_f32 v[156:157], v[120:121], v[148:149]
	v_exp_f32_e32 v150, v150
	v_exp_f32_e32 v151, v151
	v_exp_f32_e32 v152, v152
	v_exp_f32_e32 v153, v153
	v_exp_f32_e32 v154, v154
	v_exp_f32_e32 v155, v155
	v_exp_f32_e32 v156, v156
	v_exp_f32_e32 v157, v157
	v_pk_add_f32 v[150:151], v[150:151], 1.0 op_sel_hi:[1,0]
	v_pk_add_f32 v[152:153], v[152:153], 1.0 op_sel_hi:[1,0]
	v_pk_add_f32 v[154:155], v[154:155], 1.0 op_sel_hi:[1,0]
	v_pk_add_f32 v[156:157], v[156:157], 1.0 op_sel_hi:[1,0]
	v_rcp_f32_e32 v150, v150
	v_rcp_f32_e32 v151, v151
	v_rcp_f32_e32 v152, v152
	v_rcp_f32_e32 v153, v153
	v_rcp_f32_e32 v154, v154
	v_rcp_f32_e32 v155, v155
	v_rcp_f32_e32 v156, v156
	v_rcp_f32_e32 v157, v157
	v_pk_mul_f32 v[126:127], v[126:127], v[150:151]
	v_pk_mul_f32 v[128:129], v[128:129], v[152:153]
	v_pk_mul_f32 v[118:119], v[118:119], v[154:155]
	v_pk_mul_f32 v[120:121], v[120:121], v[156:157]
	v_pk_mul_f32 v[126:127], v[126:127], v[122:123]
	v_pk_mul_f32 v[128:129], v[128:129], v[124:125]
	v_pk_mul_f32 v[118:119], v[118:119], v[114:115]
	v_pk_mul_f32 v[120:121], v[120:121], v[116:117]
	v_cvt_pk_bf16_f32 v170, v126, v127
	v_cvt_pk_bf16_f32 v171, v128, v129
	v_cvt_pk_bf16_f32 v172, v118, v119
	v_cvt_pk_bf16_f32 v173, v120, v121
	global_store_dwordx4 v146, v[170:173], s[20:21]
	v_pk_mul_f32 v[150:151], v[110:111], v[148:149]
	v_pk_mul_f32 v[152:153], v[112:113], v[148:149]
	v_pk_mul_f32 v[154:155], v[102:103], v[148:149]
	v_pk_mul_f32 v[156:157], v[104:105], v[148:149]
	v_exp_f32_e32 v150, v150
	v_exp_f32_e32 v151, v151
	v_exp_f32_e32 v152, v152
	v_exp_f32_e32 v153, v153
	v_exp_f32_e32 v154, v154
	v_exp_f32_e32 v155, v155
	v_exp_f32_e32 v156, v156
	v_exp_f32_e32 v157, v157
	v_pk_add_f32 v[150:151], v[150:151], 1.0 op_sel_hi:[1,0]
	v_pk_add_f32 v[152:153], v[152:153], 1.0 op_sel_hi:[1,0]
	v_pk_add_f32 v[154:155], v[154:155], 1.0 op_sel_hi:[1,0]
	v_pk_add_f32 v[156:157], v[156:157], 1.0 op_sel_hi:[1,0]
	v_rcp_f32_e32 v150, v150
	v_rcp_f32_e32 v151, v151
	v_rcp_f32_e32 v152, v152
	v_rcp_f32_e32 v153, v153
	v_rcp_f32_e32 v154, v154
	v_rcp_f32_e32 v155, v155
	v_rcp_f32_e32 v156, v156
	v_rcp_f32_e32 v157, v157
	v_pk_mul_f32 v[110:111], v[110:111], v[150:151]
	v_pk_mul_f32 v[112:113], v[112:113], v[152:153]
	v_pk_mul_f32 v[102:103], v[102:103], v[154:155]
	v_pk_mul_f32 v[104:105], v[104:105], v[156:157]
	v_pk_mul_f32 v[110:111], v[110:111], v[106:107]
	v_pk_mul_f32 v[112:113], v[112:113], v[108:109]
	v_pk_mul_f32 v[102:103], v[102:103], v[98:99]
	v_pk_mul_f32 v[104:105], v[104:105], v[100:101]
	v_cvt_pk_bf16_f32 v174, v110, v111
	v_cvt_pk_bf16_f32 v175, v112, v113
	v_cvt_pk_bf16_f32 v176, v102, v103
	v_cvt_pk_bf16_f32 v177, v104, v105
	v_add_u32_e32 v179, 0x16000, v146
	global_store_dwordx4 v179, v[174:177], s[20:21]
	v_pk_mul_f32 v[150:151], v[94:95], v[148:149]
	v_pk_mul_f32 v[152:153], v[96:97], v[148:149]
	v_pk_mul_f32 v[154:155], v[86:87], v[148:149]
	v_pk_mul_f32 v[156:157], v[88:89], v[148:149]
	v_exp_f32_e32 v150, v150
	v_exp_f32_e32 v151, v151
	v_exp_f32_e32 v152, v152
	v_exp_f32_e32 v153, v153
	v_exp_f32_e32 v154, v154
	v_exp_f32_e32 v155, v155
	v_exp_f32_e32 v156, v156
	v_exp_f32_e32 v157, v157
	v_pk_add_f32 v[150:151], v[150:151], 1.0 op_sel_hi:[1,0]
	v_pk_add_f32 v[152:153], v[152:153], 1.0 op_sel_hi:[1,0]
	v_pk_add_f32 v[154:155], v[154:155], 1.0 op_sel_hi:[1,0]
	v_pk_add_f32 v[156:157], v[156:157], 1.0 op_sel_hi:[1,0]
	v_rcp_f32_e32 v150, v150
	v_rcp_f32_e32 v151, v151
	v_rcp_f32_e32 v152, v152
	v_rcp_f32_e32 v153, v153
	v_rcp_f32_e32 v154, v154
	v_rcp_f32_e32 v155, v155
	v_rcp_f32_e32 v156, v156
	v_rcp_f32_e32 v157, v157
	v_pk_mul_f32 v[94:95], v[94:95], v[150:151]
	v_pk_mul_f32 v[96:97], v[96:97], v[152:153]
	v_pk_mul_f32 v[86:87], v[86:87], v[154:155]
	v_pk_mul_f32 v[88:89], v[88:89], v[156:157]
	v_pk_mul_f32 v[94:95], v[94:95], v[90:91]
	v_pk_mul_f32 v[96:97], v[96:97], v[92:93]
	v_pk_mul_f32 v[86:87], v[86:87], v[82:83]
	v_pk_mul_f32 v[88:89], v[88:89], v[84:85]
	v_cvt_pk_bf16_f32 v170, v94, v95
	v_cvt_pk_bf16_f32 v171, v96, v97
	v_cvt_pk_bf16_f32 v172, v86, v87
	v_cvt_pk_bf16_f32 v173, v88, v89
	v_add_u32_e32 v178, 0x2c000, v146
	global_store_dwordx4 v178, v[170:173], s[20:21]
	v_pk_mul_f32 v[150:151], v[78:79], v[148:149]
	v_pk_mul_f32 v[152:153], v[80:81], v[148:149]
	v_pk_mul_f32 v[154:155], v[70:71], v[148:149]
	v_pk_mul_f32 v[156:157], v[72:73], v[148:149]
	v_exp_f32_e32 v150, v150
	v_exp_f32_e32 v151, v151
	v_exp_f32_e32 v152, v152
	v_exp_f32_e32 v153, v153
	v_exp_f32_e32 v154, v154
	v_exp_f32_e32 v155, v155
	v_exp_f32_e32 v156, v156
	v_exp_f32_e32 v157, v157
	v_pk_add_f32 v[150:151], v[150:151], 1.0 op_sel_hi:[1,0]
	v_pk_add_f32 v[152:153], v[152:153], 1.0 op_sel_hi:[1,0]
	v_pk_add_f32 v[154:155], v[154:155], 1.0 op_sel_hi:[1,0]
	v_pk_add_f32 v[156:157], v[156:157], 1.0 op_sel_hi:[1,0]
	v_rcp_f32_e32 v150, v150
	v_rcp_f32_e32 v151, v151
	v_rcp_f32_e32 v152, v152
	v_rcp_f32_e32 v153, v153
	v_rcp_f32_e32 v154, v154
	v_rcp_f32_e32 v155, v155
	v_rcp_f32_e32 v156, v156
	v_rcp_f32_e32 v157, v157
	v_pk_mul_f32 v[78:79], v[78:79], v[150:151]
	v_pk_mul_f32 v[80:81], v[80:81], v[152:153]
	v_pk_mul_f32 v[70:71], v[70:71], v[154:155]
	v_pk_mul_f32 v[72:73], v[72:73], v[156:157]
	v_pk_mul_f32 v[78:79], v[78:79], v[74:75]
	v_pk_mul_f32 v[80:81], v[80:81], v[76:77]
	v_pk_mul_f32 v[70:71], v[70:71], v[66:67]
	v_pk_mul_f32 v[72:73], v[72:73], v[68:69]
	v_cvt_pk_bf16_f32 v174, v78, v79
	v_cvt_pk_bf16_f32 v175, v80, v81
	v_cvt_pk_bf16_f32 v176, v70, v71
	v_cvt_pk_bf16_f32 v177, v72, v73
	v_add_u32_e32 v179, 0x42000, v146
	global_store_dwordx4 v179, v[174:177], s[20:21]
	v_pk_mul_f32 v[150:151], v[62:63], v[148:149]
	v_pk_mul_f32 v[152:153], v[64:65], v[148:149]
	v_pk_mul_f32 v[154:155], v[54:55], v[148:149]
	v_pk_mul_f32 v[156:157], v[56:57], v[148:149]
	v_exp_f32_e32 v150, v150
	v_exp_f32_e32 v151, v151
	v_exp_f32_e32 v152, v152
	v_exp_f32_e32 v153, v153
	v_exp_f32_e32 v154, v154
	v_exp_f32_e32 v155, v155
	v_exp_f32_e32 v156, v156
	v_exp_f32_e32 v157, v157
	v_pk_add_f32 v[150:151], v[150:151], 1.0 op_sel_hi:[1,0]
	v_pk_add_f32 v[152:153], v[152:153], 1.0 op_sel_hi:[1,0]
	v_pk_add_f32 v[154:155], v[154:155], 1.0 op_sel_hi:[1,0]
	v_pk_add_f32 v[156:157], v[156:157], 1.0 op_sel_hi:[1,0]
	v_rcp_f32_e32 v150, v150
	v_rcp_f32_e32 v151, v151
	v_rcp_f32_e32 v152, v152
	v_rcp_f32_e32 v153, v153
	v_rcp_f32_e32 v154, v154
	v_rcp_f32_e32 v155, v155
	v_rcp_f32_e32 v156, v156
	v_rcp_f32_e32 v157, v157
	v_pk_mul_f32 v[62:63], v[62:63], v[150:151]
	v_pk_mul_f32 v[64:65], v[64:65], v[152:153]
	v_pk_mul_f32 v[54:55], v[54:55], v[154:155]
	v_pk_mul_f32 v[56:57], v[56:57], v[156:157]
	v_pk_mul_f32 v[62:63], v[62:63], v[58:59]
	v_pk_mul_f32 v[64:65], v[64:65], v[60:61]
	v_pk_mul_f32 v[54:55], v[54:55], v[50:51]
	v_pk_mul_f32 v[56:57], v[56:57], v[52:53]
	v_cvt_pk_bf16_f32 v170, v62, v63
	v_cvt_pk_bf16_f32 v171, v64, v65
	v_cvt_pk_bf16_f32 v172, v54, v55
	v_cvt_pk_bf16_f32 v173, v56, v57
	v_add_u32_e32 v178, 0xb0000, v146
	global_store_dwordx4 v178, v[170:173], s[20:21]
	v_pk_mul_f32 v[150:151], v[46:47], v[148:149]
	v_pk_mul_f32 v[152:153], v[48:49], v[148:149]
	v_pk_mul_f32 v[154:155], v[38:39], v[148:149]
	v_pk_mul_f32 v[156:157], v[40:41], v[148:149]
	v_exp_f32_e32 v150, v150
	v_exp_f32_e32 v151, v151
	v_exp_f32_e32 v152, v152
	v_exp_f32_e32 v153, v153
	v_exp_f32_e32 v154, v154
	v_exp_f32_e32 v155, v155
	v_exp_f32_e32 v156, v156
	v_exp_f32_e32 v157, v157
	v_pk_add_f32 v[150:151], v[150:151], 1.0 op_sel_hi:[1,0]
	v_pk_add_f32 v[152:153], v[152:153], 1.0 op_sel_hi:[1,0]
	v_pk_add_f32 v[154:155], v[154:155], 1.0 op_sel_hi:[1,0]
	v_pk_add_f32 v[156:157], v[156:157], 1.0 op_sel_hi:[1,0]
	v_rcp_f32_e32 v150, v150
	v_rcp_f32_e32 v151, v151
	v_rcp_f32_e32 v152, v152
	v_rcp_f32_e32 v153, v153
	v_rcp_f32_e32 v154, v154
	v_rcp_f32_e32 v155, v155
	v_rcp_f32_e32 v156, v156
	v_rcp_f32_e32 v157, v157
	v_pk_mul_f32 v[46:47], v[46:47], v[150:151]
	v_pk_mul_f32 v[48:49], v[48:49], v[152:153]
	v_pk_mul_f32 v[38:39], v[38:39], v[154:155]
	v_pk_mul_f32 v[40:41], v[40:41], v[156:157]
	v_pk_mul_f32 v[46:47], v[46:47], v[42:43]
	v_pk_mul_f32 v[48:49], v[48:49], v[44:45]
	v_pk_mul_f32 v[38:39], v[38:39], v[34:35]
	v_pk_mul_f32 v[40:41], v[40:41], v[36:37]
	v_cvt_pk_bf16_f32 v174, v46, v47
	v_cvt_pk_bf16_f32 v175, v48, v49
	v_cvt_pk_bf16_f32 v176, v38, v39
	v_cvt_pk_bf16_f32 v177, v40, v41
	v_add_u32_e32 v179, 0xc6000, v146
	global_store_dwordx4 v179, v[174:177], s[20:21]
	v_pk_mul_f32 v[150:151], v[30:31], v[148:149]
	v_pk_mul_f32 v[152:153], v[32:33], v[148:149]
	v_pk_mul_f32 v[154:155], v[22:23], v[148:149]
	v_pk_mul_f32 v[156:157], v[24:25], v[148:149]
	v_exp_f32_e32 v150, v150
	v_exp_f32_e32 v151, v151
	v_exp_f32_e32 v152, v152
	v_exp_f32_e32 v153, v153
	v_exp_f32_e32 v154, v154
	v_exp_f32_e32 v155, v155
	v_exp_f32_e32 v156, v156
	v_exp_f32_e32 v157, v157
	v_pk_add_f32 v[150:151], v[150:151], 1.0 op_sel_hi:[1,0]
	v_pk_add_f32 v[152:153], v[152:153], 1.0 op_sel_hi:[1,0]
	v_pk_add_f32 v[154:155], v[154:155], 1.0 op_sel_hi:[1,0]
	v_pk_add_f32 v[156:157], v[156:157], 1.0 op_sel_hi:[1,0]
	v_rcp_f32_e32 v150, v150
	v_rcp_f32_e32 v151, v151
	v_rcp_f32_e32 v152, v152
	v_rcp_f32_e32 v153, v153
	v_rcp_f32_e32 v154, v154
	v_rcp_f32_e32 v155, v155
	v_rcp_f32_e32 v156, v156
	v_rcp_f32_e32 v157, v157
	v_pk_mul_f32 v[30:31], v[30:31], v[150:151]
	v_pk_mul_f32 v[32:33], v[32:33], v[152:153]
	v_pk_mul_f32 v[22:23], v[22:23], v[154:155]
	v_pk_mul_f32 v[24:25], v[24:25], v[156:157]
	v_pk_mul_f32 v[30:31], v[30:31], v[26:27]
	v_pk_mul_f32 v[32:33], v[32:33], v[28:29]
	v_pk_mul_f32 v[22:23], v[22:23], v[18:19]
	v_pk_mul_f32 v[24:25], v[24:25], v[20:21]
	v_cvt_pk_bf16_f32 v170, v30, v31
	v_cvt_pk_bf16_f32 v171, v32, v33
	v_cvt_pk_bf16_f32 v172, v22, v23
	v_cvt_pk_bf16_f32 v173, v24, v25
	v_add_u32_e32 v178, 0xdc000, v146
	global_store_dwordx4 v178, v[170:173], s[20:21]
	v_pk_mul_f32 v[150:151], v[14:15], v[148:149]
	v_pk_mul_f32 v[152:153], v[16:17], v[148:149]
	v_pk_mul_f32 v[154:155], v[6:7], v[148:149]
	v_pk_mul_f32 v[156:157], v[8:9], v[148:149]
	v_exp_f32_e32 v150, v150
	v_exp_f32_e32 v151, v151
	v_exp_f32_e32 v152, v152
	v_exp_f32_e32 v153, v153
	v_exp_f32_e32 v154, v154
	v_exp_f32_e32 v155, v155
	v_exp_f32_e32 v156, v156
	v_exp_f32_e32 v157, v157
	v_pk_add_f32 v[150:151], v[150:151], 1.0 op_sel_hi:[1,0]
	v_pk_add_f32 v[152:153], v[152:153], 1.0 op_sel_hi:[1,0]
	v_pk_add_f32 v[154:155], v[154:155], 1.0 op_sel_hi:[1,0]
	v_pk_add_f32 v[156:157], v[156:157], 1.0 op_sel_hi:[1,0]
	v_rcp_f32_e32 v150, v150
	v_rcp_f32_e32 v151, v151
	v_rcp_f32_e32 v152, v152
	v_rcp_f32_e32 v153, v153
	v_rcp_f32_e32 v154, v154
	v_rcp_f32_e32 v155, v155
	v_rcp_f32_e32 v156, v156
	v_rcp_f32_e32 v157, v157
	v_pk_mul_f32 v[14:15], v[14:15], v[150:151]
	v_pk_mul_f32 v[16:17], v[16:17], v[152:153]
	v_pk_mul_f32 v[6:7], v[6:7], v[154:155]
	v_pk_mul_f32 v[8:9], v[8:9], v[156:157]
	v_pk_mul_f32 v[14:15], v[14:15], v[10:11]
	v_pk_mul_f32 v[16:17], v[16:17], v[12:13]
	v_pk_mul_f32 v[6:7], v[6:7], v[2:3]
	v_pk_mul_f32 v[8:9], v[8:9], v[4:5]
	v_cvt_pk_bf16_f32 v174, v14, v15
	v_cvt_pk_bf16_f32 v175, v16, v17
	v_cvt_pk_bf16_f32 v176, v6, v7
	v_cvt_pk_bf16_f32 v177, v8, v9
	v_add_u32_e32 v179, 0xf2000, v146
	global_store_dwordx4 v179, v[174:177], s[20:21]
	s_andn2_b64 vcc, exec, s[6:7]
	s_mov_b64 s[20:21], -1
	s_cbranch_vccnz .LBB0_680
	s_andn2_b64 vcc, exec, s[8:9]
	s_cbranch_vccnz .LBB0_679
	s_barrier
	s_branch .LBB0_679
